# v8 + second-half residual loads of the EpiRes epilogues (phases 2,7,9) issued with the first half
# speedup vs baseline: 1.0073x; 1.0018x over previous
; __device__ __forceinline__ unsigned cvt_pk_bf16(float lo, float hi) { unsigned r; asm("v_cvt_pk_bf16_f32 %0, %1, %2" : "=v"(r) : "v"(lo), "v"(hi)); return r; }
; __device__ __forceinline__ float bf_lo(unsigned u) { return __uint_as_float(u << 16); }
; __device__ __forceinline__ float bf_hi(unsigned u) { return __uint_as_float(u & 0xffff0000u); }
;     __device__ __forceinline__ bool operator()(AccT& acc, const pg8::Unit& u, int wr, int wc, int fr, int fq, const float (&)[8]) const {
;         const int row0 = u.pm * 256 + wr * 64 + fr, colt = u.pn * 256 + wc * 32 + 8 * fq;
; #pragma unroll
;         for (int ai = 0; ai < 2; ++ai) {
;             f32x4 xv[4][2][2];
; #pragma unroll
;             for (int m = 0; m < 4; ++m)
; #pragma unroll
;                 for (int bj = 0; bj < 2; ++bj) {
;                     const int row = row0 + ai * 128 + m * 16, col = colt + bj * 128;
;                     {   const u32x4 xw = *(const u32x4*)(xb + (size_t)row * D + col);
;                         xv[m][bj][0] = (f32x4){bf_lo(xw.x), bf_hi(xw.x), bf_lo(xw.y), bf_hi(xw.y)}; xv[m][bj][1] = (f32x4){bf_lo(xw.z), bf_hi(xw.z), bf_lo(xw.w), bf_hi(xw.w)}; }
;                 }
; #pragma unroll
;             for (int m = 0; m < 4; ++m) {
;                 const int row = row0 + ai * 128 + m * 16; float sq = 0.f;
; #pragma unroll
;                 for (int bj = 0; bj < 2; ++bj) {
;                     const int col = colt + bj * 128; const float sc = (MODE == 1) ? 1.f : 0.5f;
;                     const f32x4 v0 = xv[m][bj][0] + sc * acc[ai][bj][m][0], v1 = xv[m][bj][1] + sc * acc[ai][bj][m][1];
;                     if (MODE == 2) { float* o = out + (size_t)row * D + col; __builtin_nontemporal_store(v0, (f32x4*)o); __builtin_nontemporal_store(v1, (f32x4*)(o + 4)); }
;                     if (MODE != 2) {
;                         sq += (v0[0] * v0[0] + v0[1] * v0[1]) + (v0[2] * v0[2] + v0[3] * v0[3]) + (v1[0] * v1[0] + v1[1] * v1[1]) + (v1[2] * v1[2] + v1[3] * v1[3]);
;                         u32x4 w; w.x = cvt_pk_bf16(v0[0], v0[1]); w.y = cvt_pk_bf16(v0[2], v0[3]); w.z = cvt_pk_bf16(v1[0], v1[1]); w.w = cvt_pk_bf16(v1[2], v1[3]);
;                         *(u32x4*)(xb + (size_t)row * D + col) = w; }
;                 }
;                 if (MODE != 2) { sq += __shfl_xor(sq, 16); sq += __shfl_xor(sq, 32); if (fq == 0) unsafeAtomicAdd(ss + row, sq); }
.LBB0_329:
	v_lshl_add_u32 v172, s44, 8, v1
	v_lshl_or_b32 v130, s45, 8, v187
	v_ashrrev_i32_e32 v173, 31, v172
	v_ashrrev_i32_e32 v131, 31, v130
	v_lshlrev_b64 v[132:133], 11, v[172:173]
	v_lshl_add_u64 v[132:133], s[60:61], 0, v[132:133]
	v_lshlrev_b64 v[170:171], 1, v[130:131]
	v_lshl_add_u64 v[204:205], v[132:133], 0, v[170:171]
	global_load_dwordx4 v[196:199], v[204:205], off
	global_load_dwordx4 v[200:203], v[204:205], off offset:256
	v_or_b32_e32 v182, 16, v172
	v_or_b32_e32 v178, 32, v172
	v_or_b32_e32 v174, 48, v172
	v_ashrrev_i32_e32 v183, 31, v182
	v_ashrrev_i32_e32 v179, 31, v178
	v_ashrrev_i32_e32 v175, 31, v174
	v_lshlrev_b64 v[130:131], 11, v[182:183]
	v_lshlrev_b64 v[132:133], 11, v[178:179]
	v_lshlrev_b64 v[134:135], 11, v[174:175]
	v_lshl_add_u64 v[130:131], s[60:61], 0, v[130:131]
	v_lshl_add_u64 v[132:133], s[60:61], 0, v[132:133]
	v_lshl_add_u64 v[134:135], s[60:61], 0, v[134:135]
	v_lshl_add_u64 v[184:185], v[130:131], 0, v[170:171]
	v_lshl_add_u64 v[180:181], v[132:133], 0, v[170:171]
	v_lshl_add_u64 v[176:177], v[134:135], 0, v[170:171]
	global_load_dwordx4 v[150:153], v[184:185], off
	global_load_dwordx4 v[146:149], v[184:185], off offset:256
	global_load_dwordx4 v[142:145], v[180:181], off
	global_load_dwordx4 v[138:141], v[180:181], off offset:256
	global_load_dwordx4 v[134:137], v[176:177], off
	global_load_dwordx4 v[130:133], v[176:177], off offset:256
	s_add_u32 s98, s60, 0x40000
	s_addc_u32 s99, s61, 0
	v_lshl_add_u32 v232, v172, 11, v170
	v_add_u32_e32 v240, 0x8000, v232
	v_add_u32_e32 v248, 0x10000, v232
	global_load_dwordx4 v[228:231], v232, s[98:99]
	global_load_dwordx4 v[232:235], v232, s[98:99] offset:256
	global_load_dwordx4 v[236:239], v240, s[98:99]
	global_load_dwordx4 v[240:243], v240, s[98:99] offset:256
	global_load_dwordx4 v[244:247], v248, s[98:99]
	global_load_dwordx4 v[248:251], v248, s[98:99] offset:256
	v_and_b32_e32 v193, 64, v191
	v_xor_b32_e32 v192, 16, v191
	v_add_u32_e32 v193, 64, v193
	v_xor_b32_e32 v195, 32, v191
	v_cmp_lt_i32_e32 vcc, v192, v193
	s_waitcnt vmcnt(6)
	v_lshlrev_b32_e32 v206, 16, v196
	v_and_b32_e32 v207, 0xffff0000, v196
	v_lshlrev_b32_e32 v196, 16, v197
	v_and_b32_e32 v197, 0xffff0000, v197
	v_lshlrev_b32_e32 v210, 16, v200
	v_and_b32_e32 v211, 0xffff0000, v200
	v_lshlrev_b32_e32 v200, 16, v201
	v_and_b32_e32 v201, 0xffff0000, v201
	v_lshlrev_b32_e32 v208, 16, v198
	v_and_b32_e32 v209, 0xffff0000, v198
	v_lshlrev_b32_e32 v198, 16, v199
	v_and_b32_e32 v199, 0xffff0000, v199
	v_lshlrev_b32_e32 v212, 16, v202
	v_and_b32_e32 v213, 0xffff0000, v202
	v_lshlrev_b32_e32 v202, 16, v203
	v_and_b32_e32 v203, 0xffff0000, v203
	v_pk_fma_f32 v[128:129], v[128:129], 0.5, v[196:197] op_sel_hi:[1,0,1]
	v_pk_fma_f32 v[126:127], v[126:127], 0.5, v[206:207] op_sel_hi:[1,0,1]
	v_pk_fma_f32 v[120:121], v[120:121], 0.5, v[200:201] op_sel_hi:[1,0,1]
	v_pk_fma_f32 v[118:119], v[118:119], 0.5, v[210:211] op_sel_hi:[1,0,1]
	v_cndmask_b32_e32 v192, v191, v192, vcc
	v_cmp_lt_i32_e32 vcc, v195, v193
	v_pk_fma_f32 v[124:125], v[124:125], 0.5, v[198:199] op_sel_hi:[1,0,1]
	v_pk_fma_f32 v[122:123], v[122:123], 0.5, v[208:209] op_sel_hi:[1,0,1]
	v_pk_fma_f32 v[196:197], v[116:117], 0.5, v[202:203] op_sel_hi:[1,0,1]
	v_pk_fma_f32 v[198:199], v[114:115], 0.5, v[212:213] op_sel_hi:[1,0,1]
	v_mul_f32_e32 v116, v127, v127
	v_mul_f32_e32 v117, v129, v129
	v_cvt_pk_bf16_f32 v114, v126, v127
	v_cvt_pk_bf16_f32 v115, v128, v129
	v_mul_f32_e32 v127, v119, v119
	v_mul_f32_e32 v129, v121, v121
	v_cndmask_b32_e32 v193, v191, v195, vcc
	v_mul_f32_e32 v195, v123, v123
	v_mul_f32_e32 v201, v199, v199
	v_fmac_f32_e32 v116, v126, v126
	v_fmac_f32_e32 v117, v128, v128
	v_fmac_f32_e32 v127, v118, v118
	v_fmac_f32_e32 v129, v120, v120
	v_mul_f32_e32 v200, v125, v125
	v_mul_f32_e32 v202, v197, v197
	v_fmac_f32_e32 v195, v122, v122
	v_fmac_f32_e32 v201, v198, v198
	v_add_f32_e32 v116, v116, v117
	v_add_f32_e32 v117, v127, v129
	v_fmac_f32_e32 v200, v124, v124
	v_fmac_f32_e32 v202, v196, v196
	v_add_f32_e32 v116, v195, v116
	v_add_f32_e32 v117, v201, v117
	v_add_f32_e32 v116, v200, v116
	v_add_f32_e32 v117, v202, v117
	v_lshlrev_b32_e32 v192, 2, v192
	v_add_f32_e32 v126, v116, v117
	ds_bpermute_b32 v127, v192, v126
	v_cvt_pk_bf16_f32 v116, v122, v123
	v_cvt_pk_bf16_f32 v117, v124, v125
	global_store_dwordx4 v[204:205], v[114:117], off
	v_cvt_pk_bf16_f32 v118, v118, v119
	v_cvt_pk_bf16_f32 v119, v120, v121
	v_cvt_pk_bf16_f32 v120, v198, v199
	v_cvt_pk_bf16_f32 v121, v196, v197
	global_store_dwordx4 v[204:205], v[118:121], off offset:256
	s_waitcnt lgkmcnt(0)
	v_add_f32_e32 v115, v126, v127
	v_lshlrev_b32_e32 v114, 2, v193
	ds_bpermute_b32 v116, v114, v115
	s_and_saveexec_b64 s[18:19], s[0:1]
	s_cbranch_execz .LBB0_331
	s_waitcnt lgkmcnt(0)
	v_add_f32_e32 v115, v115, v116
	v_lshl_add_u64 v[116:117], v[172:173], 2, s[34:35]
	global_atomic_add_f32 v[116:117], v115, off

; __device__ __forceinline__ unsigned cvt_pk_bf16(float lo, float hi) { unsigned r; asm("v_cvt_pk_bf16_f32 %0, %1, %2" : "=v"(r) : "v"(lo), "v"(hi)); return r; }
; __device__ __forceinline__ float bf_lo(unsigned u) { return __uint_as_float(u << 16); }
; __device__ __forceinline__ float bf_hi(unsigned u) { return __uint_as_float(u & 0xffff0000u); }
;     __device__ __forceinline__ bool operator()(AccT& acc, const pg8::Unit& u, int wr, int wc, int fr, int fq, const float (&)[8]) const {
;     ...
;         for (int ai = 0; ai < 2; ++ai) {
;             f32x4 xv[4][2][2];
; #pragma unroll
;             for (int m = 0; m < 4; ++m)
; #pragma unroll
;                 for (int bj = 0; bj < 2; ++bj) {
;                     const int row = row0 + ai * 128 + m * 16, col = colt + bj * 128;
;                     {   const u32x4 xw = *(const u32x4*)(xb + (size_t)row * D + col);
;                         xv[m][bj][0] = (f32x4){bf_lo(xw.x), bf_hi(xw.x), bf_lo(xw.y), bf_hi(xw.y)}; xv[m][bj][1] = (f32x4){bf_lo(xw.z), bf_hi(xw.z), bf_lo(xw.w), bf_hi(xw.w)}; }
;                 }
; #pragma unroll
;             for (int m = 0; m < 4; ++m) {
;                 const int row = row0 + ai * 128 + m * 16; float sq = 0.f;
; #pragma unroll
;                 for (int bj = 0; bj < 2; ++bj) {
;                     const int col = colt + bj * 128; const float sc = (MODE == 1) ? 1.f : 0.5f;
;                     const f32x4 v0 = xv[m][bj][0] + sc * acc[ai][bj][m][0], v1 = xv[m][bj][1] + sc * acc[ai][bj][m][1];
;                     if (MODE == 2) { float* o = out + (size_t)row * D + col; __builtin_nontemporal_store(v0, (f32x4*)o); __builtin_nontemporal_store(v1, (f32x4*)(o + 4)); }
;                     if (MODE != 2) {
;                         sq += (v0[0] * v0[0] + v0[1] * v0[1]) + (v0[2] * v0[2] + v0[3] * v0[3]) + (v1[0] * v1[0] + v1[1] * v1[1]) + (v1[2] * v1[2] + v1[3] * v1[3]);
;                         u32x4 w; w.x = cvt_pk_bf16(v0[0], v0[1]); w.y = cvt_pk_bf16(v0[2], v0[3]); w.z = cvt_pk_bf16(v1[0], v1[1]); w.w = cvt_pk_bf16(v1[2], v1[3]);
;                         *(u32x4*)(xb + (size_t)row * D + col) = w; }
;                 }
;                 if (MODE != 2) { sq += __shfl_xor(sq, 16); sq += __shfl_xor(sq, 32); if (fq == 0) unsafeAtomicAdd(ss + row, sq); }
.LBB0_337:
	s_or_b64 exec, exec, s[18:19]
	v_add_u32_e32 v102, 0x80, v172
	v_ashrrev_i32_e32 v103, 31, v102
	s_waitcnt lgkmcnt(0)
	v_lshlrev_b64 v[66:67], 11, v[102:103]
	v_lshl_add_u64 v[66:67], s[60:61], 0, v[66:67]
	v_lshl_add_u64 v[112:113], v[66:67], 0, v[170:171]
	v_add_u32_e32 v98, 0x90, v172
	v_add_u32_e32 v94, 0xa0, v172
	v_add_u32_e32 v90, 0xb0, v172
	v_ashrrev_i32_e32 v99, 31, v98
	v_ashrrev_i32_e32 v95, 31, v94
	v_ashrrev_i32_e32 v91, 31, v90
	v_lshlrev_b64 v[66:67], 11, v[98:99]
	v_lshlrev_b64 v[68:69], 11, v[94:95]
	v_lshlrev_b64 v[70:71], 11, v[90:91]
	v_lshl_add_u64 v[66:67], s[60:61], 0, v[66:67]
	v_lshl_add_u64 v[68:69], s[60:61], 0, v[68:69]
	v_lshl_add_u64 v[70:71], s[60:61], 0, v[70:71]
	v_lshl_add_u64 v[100:101], v[66:67], 0, v[170:171]
	v_lshl_add_u64 v[96:97], v[68:69], 0, v[170:171]
	v_lshl_add_u64 v[92:93], v[70:71], 0, v[170:171]
	global_load_dwordx4 v[70:73], v[92:93], off
	global_load_dwordx4 v[66:69], v[92:93], off offset:256
	s_waitcnt vmcnt(10)
	v_mov_b32_e32 v104, v228
	v_mov_b32_e32 v105, v229
	v_mov_b32_e32 v106, v230
	v_mov_b32_e32 v107, v231
	v_mov_b32_e32 v108, v232
	v_mov_b32_e32 v109, v233
	v_mov_b32_e32 v110, v234
	v_mov_b32_e32 v111, v235
	v_mov_b32_e32 v86, v236
	v_mov_b32_e32 v87, v237
	v_mov_b32_e32 v88, v238
	v_mov_b32_e32 v89, v239
	v_mov_b32_e32 v82, v240
	v_mov_b32_e32 v83, v241
	v_mov_b32_e32 v84, v242
	v_mov_b32_e32 v85, v243
	v_mov_b32_e32 v78, v244
	v_mov_b32_e32 v79, v245
	v_mov_b32_e32 v80, v246
	v_mov_b32_e32 v81, v247
	v_mov_b32_e32 v74, v248
	v_mov_b32_e32 v75, v249
	v_mov_b32_e32 v76, v250
	v_mov_b32_e32 v77, v251
	s_waitcnt vmcnt(7)
	v_lshlrev_b32_e32 v116, 16, v104
	v_and_b32_e32 v117, 0xffff0000, v104
	v_lshlrev_b32_e32 v104, 16, v105
	v_and_b32_e32 v105, 0xffff0000, v105
	s_waitcnt vmcnt(6)
	v_lshlrev_b32_e32 v120, 16, v108
	v_and_b32_e32 v121, 0xffff0000, v108
	v_lshlrev_b32_e32 v108, 16, v109
	v_and_b32_e32 v109, 0xffff0000, v109
	v_lshlrev_b32_e32 v118, 16, v106
	v_and_b32_e32 v119, 0xffff0000, v106
	v_lshlrev_b32_e32 v106, 16, v107
	v_and_b32_e32 v107, 0xffff0000, v107
	v_lshlrev_b32_e32 v122, 16, v110
	v_and_b32_e32 v123, 0xffff0000, v110
	v_lshlrev_b32_e32 v110, 16, v111
	v_and_b32_e32 v111, 0xffff0000, v111
	v_pk_fma_f32 v[64:65], v[64:65], 0.5, v[104:105] op_sel_hi:[1,0,1]
	v_pk_fma_f32 v[62:63], v[62:63], 0.5, v[116:117] op_sel_hi:[1,0,1]
	v_pk_fma_f32 v[56:57], v[56:57], 0.5, v[108:109] op_sel_hi:[1,0,1]
	v_pk_fma_f32 v[54:55], v[54:55], 0.5, v[120:121] op_sel_hi:[1,0,1]
	v_pk_fma_f32 v[60:61], v[60:61], 0.5, v[106:107] op_sel_hi:[1,0,1]
	v_pk_fma_f32 v[58:59], v[58:59], 0.5, v[118:119] op_sel_hi:[1,0,1]
	v_pk_fma_f32 v[104:105], v[52:53], 0.5, v[110:111] op_sel_hi:[1,0,1]
	v_pk_fma_f32 v[106:107], v[50:51], 0.5, v[122:123] op_sel_hi:[1,0,1]
	v_mul_f32_e32 v52, v63, v63
	v_mul_f32_e32 v53, v65, v65
	v_cvt_pk_bf16_f32 v50, v62, v63
	v_cvt_pk_bf16_f32 v51, v64, v65
	v_mul_f32_e32 v63, v55, v55
	v_mul_f32_e32 v65, v57, v57
	v_mul_f32_e32 v108, v59, v59
	v_mul_f32_e32 v110, v107, v107
	v_fmac_f32_e32 v52, v62, v62
	v_fmac_f32_e32 v53, v64, v64
	v_fmac_f32_e32 v63, v54, v54
	v_fmac_f32_e32 v65, v56, v56
	v_mul_f32_e32 v109, v61, v61
	v_mul_f32_e32 v111, v105, v105
	v_fmac_f32_e32 v108, v58, v58
	v_fmac_f32_e32 v110, v106, v106
	v_add_f32_e32 v52, v52, v53
	v_add_f32_e32 v53, v63, v65
	v_fmac_f32_e32 v109, v60, v60
	v_fmac_f32_e32 v111, v104, v104
	v_add_f32_e32 v52, v108, v52
	v_add_f32_e32 v53, v110, v53
	v_add_f32_e32 v52, v109, v52
	v_add_f32_e32 v53, v111, v53
	v_add_f32_e32 v62, v52, v53
	ds_bpermute_b32 v63, v192, v62
	v_cvt_pk_bf16_f32 v52, v58, v59
	v_cvt_pk_bf16_f32 v53, v60, v61
	global_store_dwordx4 v[112:113], v[50:53], off
	s_waitcnt lgkmcnt(0)
	s_nop 0
	v_add_f32_e32 v50, v62, v63
	ds_bpermute_b32 v51, v114, v50
	v_cvt_pk_bf16_f32 v52, v54, v55
	v_cvt_pk_bf16_f32 v53, v56, v57
	v_cvt_pk_bf16_f32 v54, v106, v107
	v_cvt_pk_bf16_f32 v55, v104, v105
	global_store_dwordx4 v[112:113], v[52:55], off offset:256
	s_and_saveexec_b64 s[18:19], s[0:1]
	s_cbranch_execz .LBB0_339
	s_waitcnt lgkmcnt(0)
	v_add_f32_e32 v52, v50, v51
	v_lshl_add_u64 v[50:51], v[102:103], 2, s[34:35]
	global_atomic_add_f32 v[50:51], v52, off

; __device__ __forceinline__ unsigned cvt_pk_bf16(float lo, float hi) { unsigned r; asm("v_cvt_pk_bf16_f32 %0, %1, %2" : "=v"(r) : "v"(lo), "v"(hi)); return r; }
; __device__ __forceinline__ float bf_lo(unsigned u) { return __uint_as_float(u << 16); }
; __device__ __forceinline__ float bf_hi(unsigned u) { return __uint_as_float(u & 0xffff0000u); }
;     __device__ __forceinline__ bool operator()(AccT& acc, const pg8::Unit& u, int wr, int wc, int fr, int fq, const float (&)[8]) const {
;         const int row0 = u.pm * 256 + wr * 64 + fr, colt = u.pn * 256 + wc * 32 + 8 * fq;
; #pragma unroll
;         for (int ai = 0; ai < 2; ++ai) {
;             f32x4 xv[4][2][2];
; #pragma unroll
;             for (int m = 0; m < 4; ++m)
; #pragma unroll
;                 for (int bj = 0; bj < 2; ++bj) {
;                     const int row = row0 + ai * 128 + m * 16, col = colt + bj * 128;
;                     {   const u32x4 xw = *(const u32x4*)(xb + (size_t)row * D + col);
;                         xv[m][bj][0] = (f32x4){bf_lo(xw.x), bf_hi(xw.x), bf_lo(xw.y), bf_hi(xw.y)}; xv[m][bj][1] = (f32x4){bf_lo(xw.z), bf_hi(xw.z), bf_lo(xw.w), bf_hi(xw.w)}; }
;                 }
; #pragma unroll
;             for (int m = 0; m < 4; ++m) {
;                 const int row = row0 + ai * 128 + m * 16; float sq = 0.f;
; #pragma unroll
;                 for (int bj = 0; bj < 2; ++bj) {
;                     const int col = colt + bj * 128; const float sc = (MODE == 1) ? 1.f : 0.5f;
;                     const f32x4 v0 = xv[m][bj][0] + sc * acc[ai][bj][m][0], v1 = xv[m][bj][1] + sc * acc[ai][bj][m][1];
;                     if (MODE == 2) { float* o = out + (size_t)row * D + col; __builtin_nontemporal_store(v0, (f32x4*)o); __builtin_nontemporal_store(v1, (f32x4*)(o + 4)); }
;                     if (MODE != 2) {
;                         sq += (v0[0] * v0[0] + v0[1] * v0[1]) + (v0[2] * v0[2] + v0[3] * v0[3]) + (v1[0] * v1[0] + v1[1] * v1[1]) + (v1[2] * v1[2] + v1[3] * v1[3]);
;                         u32x4 w; w.x = cvt_pk_bf16(v0[0], v0[1]); w.y = cvt_pk_bf16(v0[2], v0[3]); w.z = cvt_pk_bf16(v1[0], v1[1]); w.w = cvt_pk_bf16(v1[2], v1[3]);
;                         *(u32x4*)(xb + (size_t)row * D + col) = w; }
;                 }
;                 if (MODE != 2) { sq += __shfl_xor(sq, 16); sq += __shfl_xor(sq, 32); if (fq == 0) unsafeAtomicAdd(ss + row, sq); }
.LBB0_959:
	v_lshl_add_u32 v172, s22, 8, v1
	v_lshl_or_b32 v130, s50, 8, v187
	v_ashrrev_i32_e32 v173, 31, v172
	v_ashrrev_i32_e32 v131, 31, v130
	v_lshlrev_b64 v[132:133], 11, v[172:173]
	v_lshl_add_u64 v[132:133], s[60:61], 0, v[132:133]
	v_lshlrev_b64 v[170:171], 1, v[130:131]
	v_lshl_add_u64 v[204:205], v[132:133], 0, v[170:171]
	global_load_dwordx4 v[196:199], v[204:205], off
	global_load_dwordx4 v[200:203], v[204:205], off offset:256
	v_or_b32_e32 v182, 16, v172
	v_or_b32_e32 v178, 32, v172
	v_or_b32_e32 v174, 48, v172
	v_ashrrev_i32_e32 v183, 31, v182
	v_ashrrev_i32_e32 v179, 31, v178
	v_ashrrev_i32_e32 v175, 31, v174
	v_lshlrev_b64 v[130:131], 11, v[182:183]
	v_lshlrev_b64 v[132:133], 11, v[178:179]
	v_lshlrev_b64 v[134:135], 11, v[174:175]
	v_lshl_add_u64 v[130:131], s[60:61], 0, v[130:131]
	v_lshl_add_u64 v[132:133], s[60:61], 0, v[132:133]
	v_lshl_add_u64 v[134:135], s[60:61], 0, v[134:135]
	v_lshl_add_u64 v[184:185], v[130:131], 0, v[170:171]
	v_lshl_add_u64 v[180:181], v[132:133], 0, v[170:171]
	v_lshl_add_u64 v[176:177], v[134:135], 0, v[170:171]
	global_load_dwordx4 v[150:153], v[184:185], off
	global_load_dwordx4 v[146:149], v[184:185], off offset:256
	global_load_dwordx4 v[142:145], v[180:181], off
	global_load_dwordx4 v[138:141], v[180:181], off offset:256
	global_load_dwordx4 v[134:137], v[176:177], off
	global_load_dwordx4 v[130:133], v[176:177], off offset:256
	s_add_u32 s98, s60, 0x40000
	s_addc_u32 s99, s61, 0
	v_lshl_add_u32 v232, v172, 11, v170
	v_add_u32_e32 v240, 0x8000, v232
	v_add_u32_e32 v248, 0x10000, v232
	global_load_dwordx4 v[228:231], v232, s[98:99]
	global_load_dwordx4 v[232:235], v232, s[98:99] offset:256
	global_load_dwordx4 v[236:239], v240, s[98:99]
	global_load_dwordx4 v[240:243], v240, s[98:99] offset:256
	global_load_dwordx4 v[244:247], v248, s[98:99]
	global_load_dwordx4 v[248:251], v248, s[98:99] offset:256
	v_and_b32_e32 v193, 64, v191
	v_xor_b32_e32 v192, 16, v191
	v_add_u32_e32 v193, 64, v193
	v_xor_b32_e32 v195, 32, v191
	v_cmp_lt_i32_e32 vcc, v192, v193
	s_waitcnt vmcnt(6)
	v_lshlrev_b32_e32 v206, 16, v196
	v_and_b32_e32 v207, 0xffff0000, v196
	v_lshlrev_b32_e32 v196, 16, v197
	v_and_b32_e32 v197, 0xffff0000, v197
	v_lshlrev_b32_e32 v210, 16, v200
	v_and_b32_e32 v211, 0xffff0000, v200
	v_lshlrev_b32_e32 v200, 16, v201
	v_and_b32_e32 v201, 0xffff0000, v201
	v_lshlrev_b32_e32 v208, 16, v198
	v_and_b32_e32 v209, 0xffff0000, v198
	v_lshlrev_b32_e32 v198, 16, v199
	v_and_b32_e32 v199, 0xffff0000, v199
	v_lshlrev_b32_e32 v212, 16, v202
	v_and_b32_e32 v213, 0xffff0000, v202
	v_lshlrev_b32_e32 v202, 16, v203
	v_and_b32_e32 v203, 0xffff0000, v203
	v_pk_add_f32 v[128:129], v[128:129], v[196:197]
	v_pk_add_f32 v[126:127], v[126:127], v[206:207]
	v_pk_add_f32 v[120:121], v[120:121], v[200:201]
	v_pk_add_f32 v[118:119], v[118:119], v[210:211]
	v_cndmask_b32_e32 v192, v191, v192, vcc
	v_cmp_lt_i32_e32 vcc, v195, v193
	v_pk_add_f32 v[124:125], v[124:125], v[198:199]
	v_pk_add_f32 v[122:123], v[122:123], v[208:209]
	v_pk_add_f32 v[196:197], v[116:117], v[202:203]
	v_pk_add_f32 v[198:199], v[114:115], v[212:213]
	v_mul_f32_e32 v116, v127, v127
	v_mul_f32_e32 v117, v129, v129
	v_cvt_pk_bf16_f32 v114, v126, v127
	v_cvt_pk_bf16_f32 v115, v128, v129
	v_mul_f32_e32 v127, v119, v119
	v_mul_f32_e32 v129, v121, v121
	v_cndmask_b32_e32 v193, v191, v195, vcc
	v_mul_f32_e32 v195, v123, v123
	v_mul_f32_e32 v201, v199, v199
	v_fmac_f32_e32 v116, v126, v126
	v_fmac_f32_e32 v117, v128, v128
	v_fmac_f32_e32 v127, v118, v118
	v_fmac_f32_e32 v129, v120, v120
	v_mul_f32_e32 v200, v125, v125
	v_mul_f32_e32 v202, v197, v197
	v_fmac_f32_e32 v195, v122, v122
	v_fmac_f32_e32 v201, v198, v198
	v_add_f32_e32 v116, v116, v117
	v_add_f32_e32 v117, v127, v129
	v_fmac_f32_e32 v200, v124, v124
	v_fmac_f32_e32 v202, v196, v196
	v_add_f32_e32 v116, v195, v116
	v_add_f32_e32 v117, v201, v117
	v_add_f32_e32 v116, v200, v116
	v_add_f32_e32 v117, v202, v117
	v_lshlrev_b32_e32 v192, 2, v192
	v_add_f32_e32 v126, v116, v117
	ds_bpermute_b32 v127, v192, v126
	v_cvt_pk_bf16_f32 v116, v122, v123
	v_cvt_pk_bf16_f32 v117, v124, v125
	global_store_dwordx4 v[204:205], v[114:117], off
	v_cvt_pk_bf16_f32 v118, v118, v119
	v_cvt_pk_bf16_f32 v119, v120, v121
	v_cvt_pk_bf16_f32 v120, v198, v199
	v_cvt_pk_bf16_f32 v121, v196, v197
	global_store_dwordx4 v[204:205], v[118:121], off offset:256
	s_waitcnt lgkmcnt(0)
	v_add_f32_e32 v115, v126, v127
	v_lshlrev_b32_e32 v114, 2, v193
	ds_bpermute_b32 v116, v114, v115
	s_and_saveexec_b64 s[22:23], s[0:1]
	s_cbranch_execz .LBB0_961
	s_waitcnt lgkmcnt(0)
	v_add_f32_e32 v115, v115, v116
	v_lshl_add_u64 v[116:117], v[172:173], 2, s[66:67]
	global_atomic_add_f32 v[116:117], v115, off

; __device__ __forceinline__ unsigned cvt_pk_bf16(float lo, float hi) { unsigned r; asm("v_cvt_pk_bf16_f32 %0, %1, %2" : "=v"(r) : "v"(lo), "v"(hi)); return r; }
; __device__ __forceinline__ float bf_lo(unsigned u) { return __uint_as_float(u << 16); }
; __device__ __forceinline__ float bf_hi(unsigned u) { return __uint_as_float(u & 0xffff0000u); }
;     __device__ __forceinline__ bool operator()(AccT& acc, const pg8::Unit& u, int wr, int wc, int fr, int fq, const float (&)[8]) const {
;     ...
;         for (int ai = 0; ai < 2; ++ai) {
;             f32x4 xv[4][2][2];
; #pragma unroll
;             for (int m = 0; m < 4; ++m)
; #pragma unroll
;                 for (int bj = 0; bj < 2; ++bj) {
;                     const int row = row0 + ai * 128 + m * 16, col = colt + bj * 128;
;                     {   const u32x4 xw = *(const u32x4*)(xb + (size_t)row * D + col);
;                         xv[m][bj][0] = (f32x4){bf_lo(xw.x), bf_hi(xw.x), bf_lo(xw.y), bf_hi(xw.y)}; xv[m][bj][1] = (f32x4){bf_lo(xw.z), bf_hi(xw.z), bf_lo(xw.w), bf_hi(xw.w)}; }
;                 }
; #pragma unroll
;             for (int m = 0; m < 4; ++m) {
;                 const int row = row0 + ai * 128 + m * 16; float sq = 0.f;
; #pragma unroll
;                 for (int bj = 0; bj < 2; ++bj) {
;                     const int col = colt + bj * 128; const float sc = (MODE == 1) ? 1.f : 0.5f;
;                     const f32x4 v0 = xv[m][bj][0] + sc * acc[ai][bj][m][0], v1 = xv[m][bj][1] + sc * acc[ai][bj][m][1];
;                     if (MODE == 2) { float* o = out + (size_t)row * D + col; __builtin_nontemporal_store(v0, (f32x4*)o); __builtin_nontemporal_store(v1, (f32x4*)(o + 4)); }
;                     if (MODE != 2) {
;                         sq += (v0[0] * v0[0] + v0[1] * v0[1]) + (v0[2] * v0[2] + v0[3] * v0[3]) + (v1[0] * v1[0] + v1[1] * v1[1]) + (v1[2] * v1[2] + v1[3] * v1[3]);
;                         u32x4 w; w.x = cvt_pk_bf16(v0[0], v0[1]); w.y = cvt_pk_bf16(v0[2], v0[3]); w.z = cvt_pk_bf16(v1[0], v1[1]); w.w = cvt_pk_bf16(v1[2], v1[3]);
;                         *(u32x4*)(xb + (size_t)row * D + col) = w; }
;                 }
;                 if (MODE != 2) { sq += __shfl_xor(sq, 16); sq += __shfl_xor(sq, 32); if (fq == 0) unsafeAtomicAdd(ss + row, sq); }
.LBB0_967:
	s_or_b64 exec, exec, s[22:23]
	v_add_u32_e32 v102, 0x80, v172
	v_ashrrev_i32_e32 v103, 31, v102
	s_waitcnt lgkmcnt(0)
	v_lshlrev_b64 v[66:67], 11, v[102:103]
	v_lshl_add_u64 v[66:67], s[60:61], 0, v[66:67]
	v_lshl_add_u64 v[112:113], v[66:67], 0, v[170:171]
	v_add_u32_e32 v98, 0x90, v172
	v_add_u32_e32 v94, 0xa0, v172
	v_add_u32_e32 v90, 0xb0, v172
	v_ashrrev_i32_e32 v99, 31, v98
	v_ashrrev_i32_e32 v95, 31, v94
	v_ashrrev_i32_e32 v91, 31, v90
	v_lshlrev_b64 v[66:67], 11, v[98:99]
	v_lshlrev_b64 v[68:69], 11, v[94:95]
	v_lshlrev_b64 v[70:71], 11, v[90:91]
	v_lshl_add_u64 v[66:67], s[60:61], 0, v[66:67]
	v_lshl_add_u64 v[68:69], s[60:61], 0, v[68:69]
	v_lshl_add_u64 v[70:71], s[60:61], 0, v[70:71]
	v_lshl_add_u64 v[100:101], v[66:67], 0, v[170:171]
	v_lshl_add_u64 v[96:97], v[68:69], 0, v[170:171]
	v_lshl_add_u64 v[92:93], v[70:71], 0, v[170:171]
	global_load_dwordx4 v[70:73], v[92:93], off
	global_load_dwordx4 v[66:69], v[92:93], off offset:256
	s_waitcnt vmcnt(10)
	v_mov_b32_e32 v104, v228
	v_mov_b32_e32 v105, v229
	v_mov_b32_e32 v106, v230
	v_mov_b32_e32 v107, v231
	v_mov_b32_e32 v108, v232
	v_mov_b32_e32 v109, v233
	v_mov_b32_e32 v110, v234
	v_mov_b32_e32 v111, v235
	v_mov_b32_e32 v86, v236
	v_mov_b32_e32 v87, v237
	v_mov_b32_e32 v88, v238
	v_mov_b32_e32 v89, v239
	v_mov_b32_e32 v82, v240
	v_mov_b32_e32 v83, v241
	v_mov_b32_e32 v84, v242
	v_mov_b32_e32 v85, v243
	v_mov_b32_e32 v78, v244
	v_mov_b32_e32 v79, v245
	v_mov_b32_e32 v80, v246
	v_mov_b32_e32 v81, v247
	v_mov_b32_e32 v74, v248
	v_mov_b32_e32 v75, v249
	v_mov_b32_e32 v76, v250
	v_mov_b32_e32 v77, v251
	s_waitcnt vmcnt(7)
	v_lshlrev_b32_e32 v116, 16, v104
	v_and_b32_e32 v117, 0xffff0000, v104
	v_lshlrev_b32_e32 v104, 16, v105
	v_and_b32_e32 v105, 0xffff0000, v105
	s_waitcnt vmcnt(6)
	v_lshlrev_b32_e32 v120, 16, v108
	v_and_b32_e32 v121, 0xffff0000, v108
	v_lshlrev_b32_e32 v108, 16, v109
	v_and_b32_e32 v109, 0xffff0000, v109
	v_lshlrev_b32_e32 v118, 16, v106
	v_and_b32_e32 v119, 0xffff0000, v106
	v_lshlrev_b32_e32 v106, 16, v107
	v_and_b32_e32 v107, 0xffff0000, v107
	v_lshlrev_b32_e32 v122, 16, v110
	v_and_b32_e32 v123, 0xffff0000, v110
	v_lshlrev_b32_e32 v110, 16, v111
	v_and_b32_e32 v111, 0xffff0000, v111
	v_pk_add_f32 v[64:65], v[64:65], v[104:105]
	v_pk_add_f32 v[62:63], v[62:63], v[116:117]
	v_pk_add_f32 v[56:57], v[56:57], v[108:109]
	v_pk_add_f32 v[54:55], v[54:55], v[120:121]
	v_pk_add_f32 v[60:61], v[60:61], v[106:107]
	v_pk_add_f32 v[58:59], v[58:59], v[118:119]
	v_pk_add_f32 v[104:105], v[52:53], v[110:111]
	v_pk_add_f32 v[106:107], v[50:51], v[122:123]
	v_mul_f32_e32 v52, v63, v63
	v_mul_f32_e32 v53, v65, v65
	v_cvt_pk_bf16_f32 v50, v62, v63
	v_cvt_pk_bf16_f32 v51, v64, v65
	v_mul_f32_e32 v63, v55, v55
	v_mul_f32_e32 v65, v57, v57
	v_mul_f32_e32 v108, v59, v59
	v_mul_f32_e32 v110, v107, v107
	v_fmac_f32_e32 v52, v62, v62
	v_fmac_f32_e32 v53, v64, v64
	v_fmac_f32_e32 v63, v54, v54
	v_fmac_f32_e32 v65, v56, v56
	v_mul_f32_e32 v109, v61, v61
	v_mul_f32_e32 v111, v105, v105
	v_fmac_f32_e32 v108, v58, v58
	v_fmac_f32_e32 v110, v106, v106
	v_add_f32_e32 v52, v52, v53
	v_add_f32_e32 v53, v63, v65
	v_fmac_f32_e32 v109, v60, v60
	v_fmac_f32_e32 v111, v104, v104
	v_add_f32_e32 v52, v108, v52
	v_add_f32_e32 v53, v110, v53
	v_add_f32_e32 v52, v109, v52
	v_add_f32_e32 v53, v111, v53
	v_add_f32_e32 v62, v52, v53
	ds_bpermute_b32 v63, v192, v62
	v_cvt_pk_bf16_f32 v52, v58, v59
	v_cvt_pk_bf16_f32 v53, v60, v61
	global_store_dwordx4 v[112:113], v[50:53], off
	s_waitcnt lgkmcnt(0)
	s_nop 0
	v_add_f32_e32 v50, v62, v63
	ds_bpermute_b32 v51, v114, v50
	v_cvt_pk_bf16_f32 v52, v54, v55
	v_cvt_pk_bf16_f32 v53, v56, v57
	v_cvt_pk_bf16_f32 v54, v106, v107
	v_cvt_pk_bf16_f32 v55, v104, v105
	global_store_dwordx4 v[112:113], v[52:55], off offset:256
	s_and_saveexec_b64 s[22:23], s[0:1]
	s_cbranch_execz .LBB0_969
	s_waitcnt lgkmcnt(0)
	v_add_f32_e32 v52, v50, v51
	v_lshl_add_u64 v[50:51], v[102:103], 2, s[66:67]
	global_atomic_add_f32 v[50:51], v52, off

; __device__ __forceinline__ float bf_lo(unsigned u) { return __uint_as_float(u << 16); }
; __device__ __forceinline__ float bf_hi(unsigned u) { return __uint_as_float(u & 0xffff0000u); }
;     __device__ __forceinline__ bool operator()(AccT& acc, const pg8::Unit& u, int wr, int wc, int fr, int fq, const float (&)[8]) const {
;         const int row0 = u.pm * 256 + wr * 64 + fr, colt = u.pn * 256 + wc * 32 + 8 * fq;
; #pragma unroll
;         for (int ai = 0; ai < 2; ++ai) {
;             f32x4 xv[4][2][2];
; #pragma unroll
;             for (int m = 0; m < 4; ++m)
; #pragma unroll
;                 for (int bj = 0; bj < 2; ++bj) {
;                     const int row = row0 + ai * 128 + m * 16, col = colt + bj * 128;
;                     {   const u32x4 xw = *(const u32x4*)(xb + (size_t)row * D + col);
;                         xv[m][bj][0] = (f32x4){bf_lo(xw.x), bf_hi(xw.x), bf_lo(xw.y), bf_hi(xw.y)}; xv[m][bj][1] = (f32x4){bf_lo(xw.z), bf_hi(xw.z), bf_lo(xw.w), bf_hi(xw.w)}; }
;                 }
; #pragma unroll
;             for (int m = 0; m < 4; ++m) {
;                 const int row = row0 + ai * 128 + m * 16; float sq = 0.f;
; #pragma unroll
;                 for (int bj = 0; bj < 2; ++bj) {
;                     const int col = colt + bj * 128; const float sc = (MODE == 1) ? 1.f : 0.5f;
;                     const f32x4 v0 = xv[m][bj][0] + sc * acc[ai][bj][m][0], v1 = xv[m][bj][1] + sc * acc[ai][bj][m][1];
;                     if (MODE == 2) { float* o = out + (size_t)row * D + col; __builtin_nontemporal_store(v0, (f32x4*)o); __builtin_nontemporal_store(v1, (f32x4*)(o + 4)); }
.LBB0_1139:
	v_lshl_add_u32 v144, s37, 8, v148
	v_lshl_or_b32 v186, s38, 8, v150
	v_ashrrev_i32_e32 v145, 31, v144
	v_ashrrev_i32_e32 v187, 31, v186
	v_lshlrev_b64 v[146:147], 11, v[144:145]
	v_lshl_add_u64 v[154:155], s[60:61], 0, v[146:147]
	v_lshlrev_b64 v[146:147], 1, v[186:187]
	v_or_b32_e32 v188, 16, v144
	v_lshl_add_u64 v[158:159], v[154:155], 0, v[146:147]
	v_ashrrev_i32_e32 v189, 31, v188
	global_load_dwordx4 v[154:157], v[158:159], off
	s_nop 0
	global_load_dwordx4 v[158:161], v[158:159], off offset:256
	v_lshlrev_b64 v[162:163], 11, v[188:189]
	v_lshl_add_u64 v[162:163], s[60:61], 0, v[162:163]
	v_or_b32_e32 v190, 32, v144
	v_lshl_add_u64 v[166:167], v[162:163], 0, v[146:147]
	v_ashrrev_i32_e32 v191, 31, v190
	global_load_dwordx4 v[162:165], v[166:167], off
	s_nop 0
	global_load_dwordx4 v[166:169], v[166:167], off offset:256
	v_lshlrev_b64 v[170:171], 11, v[190:191]
	v_lshl_add_u64 v[170:171], s[60:61], 0, v[170:171]
	v_or_b32_e32 v192, 48, v144
	v_lshl_add_u64 v[174:175], v[170:171], 0, v[146:147]
	v_ashrrev_i32_e32 v193, 31, v192
	global_load_dwordx4 v[170:173], v[174:175], off
	s_nop 0
	global_load_dwordx4 v[174:177], v[174:175], off offset:256
	v_lshlrev_b64 v[178:179], 11, v[192:193]
	v_lshl_add_u64 v[178:179], s[60:61], 0, v[178:179]
	v_lshl_add_u64 v[182:183], v[178:179], 0, v[146:147]
	global_load_dwordx4 v[178:181], v[182:183], off
	s_nop 0
	global_load_dwordx4 v[182:185], v[182:183], off offset:256
	s_add_u32 s98, s60, 0x40000
	s_addc_u32 s99, s61, 0
	v_lshl_add_u32 v232, v144, 11, v146
	v_add_u32_e32 v240, 0x8000, v232
	v_add_u32_e32 v248, 0x10000, v232
	global_load_dwordx4 v[228:231], v232, s[98:99]
	global_load_dwordx4 v[232:235], v232, s[98:99] offset:256
	global_load_dwordx4 v[236:239], v240, s[98:99]
	global_load_dwordx4 v[240:243], v240, s[98:99] offset:256
	global_load_dwordx4 v[244:247], v248, s[98:99]
	global_load_dwordx4 v[248:251], v248, s[98:99] offset:256
	v_lshlrev_b64 v[226:227], 12, v[144:145]
	s_andn2_b64 vcc, exec, s[0:1]
	s_mov_b64 s[0:1], -1
	s_waitcnt vmcnt(6)
	v_lshlrev_b32_e32 v194, 16, v154
	v_and_b32_e32 v195, 0xffff0000, v154
	v_lshlrev_b32_e32 v154, 16, v155
	v_and_b32_e32 v155, 0xffff0000, v155
	v_lshlrev_b32_e32 v196, 16, v156
	v_and_b32_e32 v197, 0xffff0000, v156
	v_lshlrev_b32_e32 v156, 16, v157
	v_and_b32_e32 v157, 0xffff0000, v157
	v_lshlrev_b32_e32 v198, 16, v158
	v_and_b32_e32 v199, 0xffff0000, v158
	v_lshlrev_b32_e32 v158, 16, v159
	v_and_b32_e32 v159, 0xffff0000, v159
	v_pk_fma_f32 v[126:127], v[126:127], 0.5, v[154:155] op_sel_hi:[1,0,1]
	v_pk_fma_f32 v[156:157], v[122:123], 0.5, v[156:157] op_sel_hi:[1,0,1]
	v_pk_fma_f32 v[154:155], v[120:121], 0.5, v[196:197] op_sel_hi:[1,0,1]
	v_lshl_add_u64 v[122:123], s[52:53], 0, v[226:227]
	v_lshlrev_b64 v[120:121], 2, v[186:187]
	v_lshlrev_b32_e32 v200, 16, v160
	v_and_b32_e32 v201, 0xffff0000, v160
	v_lshlrev_b32_e32 v160, 16, v161
	v_and_b32_e32 v161, 0xffff0000, v161
	v_pk_fma_f32 v[124:125], v[124:125], 0.5, v[194:195] op_sel_hi:[1,0,1]
	v_lshl_add_u64 v[122:123], v[122:123], 0, v[120:121]
	v_pk_fma_f32 v[118:119], v[118:119], 0.5, v[158:159] op_sel_hi:[1,0,1]
	v_pk_fma_f32 v[116:117], v[116:117], 0.5, v[198:199] op_sel_hi:[1,0,1]
	v_lshlrev_b32_e32 v202, 16, v162
	v_and_b32_e32 v203, 0xffff0000, v162
	global_store_dwordx4 v[122:123], v[124:127], off nt
	global_store_dwordx4 v[122:123], v[154:157], off offset:16 nt
	v_pk_fma_f32 v[110:111], v[110:111], 0.5, v[160:161] op_sel_hi:[1,0,1]
	v_pk_fma_f32 v[108:109], v[108:109], 0.5, v[200:201] op_sel_hi:[1,0,1]
	global_store_dwordx4 v[122:123], v[116:119], off offset:512 nt
	global_store_dwordx4 v[122:123], v[108:111], off offset:528 nt
	v_lshlrev_b32_e32 v162, 16, v163
	v_lshlrev_b64 v[116:117], 12, v[188:189]
	v_and_b32_e32 v163, 0xffff0000, v163
	v_lshlrev_b32_e32 v206, 16, v166
	v_and_b32_e32 v207, 0xffff0000, v166
	v_lshlrev_b32_e32 v166, 16, v167
	v_and_b32_e32 v167, 0xffff0000, v167
	v_pk_fma_f32 v[108:109], v[112:113], 0.5, v[202:203] op_sel_hi:[1,0,1]
	v_lshl_add_u64 v[112:113], s[52:53], 0, v[116:117]
	v_lshlrev_b32_e32 v204, 16, v164
	v_and_b32_e32 v205, 0xffff0000, v164
	v_lshlrev_b32_e32 v164, 16, v165
	v_and_b32_e32 v165, 0xffff0000, v165
	v_lshlrev_b32_e32 v208, 16, v168
	v_and_b32_e32 v209, 0xffff0000, v168
	v_lshlrev_b32_e32 v168, 16, v169
	v_and_b32_e32 v169, 0xffff0000, v169
	v_pk_fma_f32 v[110:111], v[114:115], 0.5, v[162:163] op_sel_hi:[1,0,1]
	v_lshl_add_u64 v[112:113], v[112:113], 0, v[120:121]
	v_pk_fma_f32 v[102:103], v[102:103], 0.5, v[166:167] op_sel_hi:[1,0,1]
	v_pk_fma_f32 v[100:101], v[100:101], 0.5, v[206:207] op_sel_hi:[1,0,1]
	v_lshlrev_b32_e32 v210, 16, v170
	v_and_b32_e32 v211, 0xffff0000, v170
	v_pk_fma_f32 v[106:107], v[106:107], 0.5, v[164:165] op_sel_hi:[1,0,1]
	v_pk_fma_f32 v[104:105], v[104:105], 0.5, v[204:205] op_sel_hi:[1,0,1]
	global_store_dwordx4 v[112:113], v[108:111], off nt
	global_store_dwordx4 v[112:113], v[104:107], off offset:16 nt
	v_pk_fma_f32 v[94:95], v[94:95], 0.5, v[168:169] op_sel_hi:[1,0,1]
	v_pk_fma_f32 v[92:93], v[92:93], 0.5, v[208:209] op_sel_hi:[1,0,1]
	global_store_dwordx4 v[112:113], v[100:103], off offset:512 nt
	global_store_dwordx4 v[112:113], v[92:95], off offset:528 nt
	v_lshlrev_b32_e32 v170, 16, v171
	v_lshlrev_b64 v[100:101], 12, v[190:191]
	v_and_b32_e32 v171, 0xffff0000, v171
	v_lshlrev_b32_e32 v214, 16, v174
	v_and_b32_e32 v215, 0xffff0000, v174
	v_lshlrev_b32_e32 v174, 16, v175
	v_and_b32_e32 v175, 0xffff0000, v175
	v_pk_fma_f32 v[92:93], v[96:97], 0.5, v[210:211] op_sel_hi:[1,0,1]
	v_lshl_add_u64 v[96:97], s[52:53], 0, v[100:101]
	v_lshlrev_b32_e32 v212, 16, v172
	v_and_b32_e32 v213, 0xffff0000, v172
; __device__ __forceinline__ unsigned cvt_pk_bf16(float lo, float hi) { unsigned r; asm("v_cvt_pk_bf16_f32 %0, %1, %2" : "=v"(r) : "v"(lo), "v"(hi)); return r; }
; __device__ __forceinline__ float bf_lo(unsigned u) { return __uint_as_float(u << 16); }
; __device__ __forceinline__ float bf_hi(unsigned u) { return __uint_as_float(u & 0xffff0000u); }
;     __device__ __forceinline__ bool operator()(AccT& acc, const pg8::Unit& u, int wr, int wc, int fr, int fq, const float (&)[8]) const {
;         const int row0 = u.pm * 256 + wr * 64 + fr, colt = u.pn * 256 + wc * 32 + 8 * fq;
; #pragma unroll
;         for (int ai = 0; ai < 2; ++ai) {
;             f32x4 xv[4][2][2];
; #pragma unroll
;             for (int m = 0; m < 4; ++m)
; #pragma unroll
;                 for (int bj = 0; bj < 2; ++bj) {
;                     const int row = row0 + ai * 128 + m * 16, col = colt + bj * 128;
;                     {   const u32x4 xw = *(const u32x4*)(xb + (size_t)row * D + col);
;                         xv[m][bj][0] = (f32x4){bf_lo(xw.x), bf_hi(xw.x), bf_lo(xw.y), bf_hi(xw.y)}; xv[m][bj][1] = (f32x4){bf_lo(xw.z), bf_hi(xw.z), bf_lo(xw.w), bf_hi(xw.w)}; }
;                 }
; #pragma unroll
;             for (int m = 0; m < 4; ++m) {
;                 const int row = row0 + ai * 128 + m * 16; float sq = 0.f;
; #pragma unroll
;                 for (int bj = 0; bj < 2; ++bj) {
;                     const int col = colt + bj * 128; const float sc = (MODE == 1) ? 1.f : 0.5f;
;                     const f32x4 v0 = xv[m][bj][0] + sc * acc[ai][bj][m][0], v1 = xv[m][bj][1] + sc * acc[ai][bj][m][1];
;                     if (MODE == 2) { float* o = out + (size_t)row * D + col; __builtin_nontemporal_store(v0, (f32x4*)o); __builtin_nontemporal_store(v1, (f32x4*)(o + 4)); }
;                     if (MODE != 2) {
;                         sq += (v0[0] * v0[0] + v0[1] * v0[1]) + (v0[2] * v0[2] + v0[3] * v0[3]) + (v1[0] * v1[0] + v1[1] * v1[1]) + (v1[2] * v1[2] + v1[3] * v1[3]);
;                         u32x4 w; w.x = cvt_pk_bf16(v0[0], v0[1]); w.y = cvt_pk_bf16(v0[2], v0[3]); w.z = cvt_pk_bf16(v1[0], v1[1]); w.w = cvt_pk_bf16(v1[2], v1[3]);
;                         *(u32x4*)(xb + (size_t)row * D + col) = w; }
	v_lshlrev_b32_e32 v172, 16, v173
	v_and_b32_e32 v173, 0xffff0000, v173
	v_lshlrev_b32_e32 v216, 16, v176
	v_and_b32_e32 v217, 0xffff0000, v176
	v_lshlrev_b32_e32 v176, 16, v177
	v_and_b32_e32 v177, 0xffff0000, v177
	v_pk_fma_f32 v[94:95], v[98:99], 0.5, v[170:171] op_sel_hi:[1,0,1]
	v_lshl_add_u64 v[96:97], v[96:97], 0, v[120:121]
	v_pk_fma_f32 v[86:87], v[86:87], 0.5, v[174:175] op_sel_hi:[1,0,1]
	v_pk_fma_f32 v[84:85], v[84:85], 0.5, v[214:215] op_sel_hi:[1,0,1]
	v_lshlrev_b32_e32 v218, 16, v178
	v_and_b32_e32 v219, 0xffff0000, v178
	v_pk_fma_f32 v[90:91], v[90:91], 0.5, v[172:173] op_sel_hi:[1,0,1]
	v_pk_fma_f32 v[88:89], v[88:89], 0.5, v[212:213] op_sel_hi:[1,0,1]
	global_store_dwordx4 v[96:97], v[92:95], off nt
	global_store_dwordx4 v[96:97], v[88:91], off offset:16 nt
	v_pk_fma_f32 v[78:79], v[78:79], 0.5, v[176:177] op_sel_hi:[1,0,1]
	v_pk_fma_f32 v[76:77], v[76:77], 0.5, v[216:217] op_sel_hi:[1,0,1]
	global_store_dwordx4 v[96:97], v[84:87], off offset:512 nt
	global_store_dwordx4 v[96:97], v[76:79], off offset:528 nt
	v_lshlrev_b32_e32 v178, 16, v179
	v_lshlrev_b64 v[84:85], 12, v[192:193]
	v_and_b32_e32 v179, 0xffff0000, v179
	v_lshlrev_b32_e32 v222, 16, v182
	v_and_b32_e32 v223, 0xffff0000, v182
	v_lshlrev_b32_e32 v182, 16, v183
	v_and_b32_e32 v183, 0xffff0000, v183
	v_lshlrev_b32_e32 v224, 16, v184
	v_and_b32_e32 v225, 0xffff0000, v184
	v_pk_fma_f32 v[76:77], v[80:81], 0.5, v[218:219] op_sel_hi:[1,0,1]
	v_lshl_add_u64 v[80:81], s[52:53], 0, v[84:85]
	v_add_u32_e32 v96, 0x80, v144
	v_lshlrev_b32_e32 v220, 16, v180
	v_and_b32_e32 v221, 0xffff0000, v180
	v_lshlrev_b32_e32 v180, 16, v181
	v_and_b32_e32 v181, 0xffff0000, v181
	v_lshlrev_b32_e32 v184, 16, v185
	v_and_b32_e32 v185, 0xffff0000, v185
	v_pk_fma_f32 v[78:79], v[82:83], 0.5, v[178:179] op_sel_hi:[1,0,1]
	v_lshl_add_u64 v[80:81], v[80:81], 0, v[120:121]
	v_pk_fma_f32 v[70:71], v[70:71], 0.5, v[182:183] op_sel_hi:[1,0,1]
	v_pk_fma_f32 v[68:69], v[68:69], 0.5, v[222:223] op_sel_hi:[1,0,1]
	v_pk_fma_f32 v[64:65], v[64:65], 0.5, v[224:225] op_sel_hi:[1,0,1]
	v_ashrrev_i32_e32 v97, 31, v96
	v_pk_fma_f32 v[74:75], v[74:75], 0.5, v[180:181] op_sel_hi:[1,0,1]
	v_pk_fma_f32 v[72:73], v[72:73], 0.5, v[220:221] op_sel_hi:[1,0,1]
	global_store_dwordx4 v[80:81], v[76:79], off nt
	global_store_dwordx4 v[80:81], v[72:75], off offset:16 nt
	v_pk_fma_f32 v[66:67], v[66:67], 0.5, v[184:185] op_sel_hi:[1,0,1]
	global_store_dwordx4 v[80:81], v[68:71], off offset:512 nt
	global_store_dwordx4 v[80:81], v[64:67], off offset:528 nt
	v_add_u32_e32 v98, 0x90, v144
	v_ashrrev_i32_e32 v99, 31, v98
	v_lshlrev_b64 v[64:65], 11, v[96:97]
	v_lshl_add_u64 v[64:65], s[60:61], 0, v[64:65]
	v_lshl_add_u64 v[68:69], v[64:65], 0, v[146:147]
	s_nop 0
	v_lshlrev_b64 v[72:73], 11, v[98:99]
	v_lshl_add_u64 v[72:73], s[60:61], 0, v[72:73]
	v_add_u32_e32 v100, 0xa0, v144
	v_lshl_add_u64 v[80:81], v[72:73], 0, v[146:147]
	v_ashrrev_i32_e32 v101, 31, v100
	v_lshlrev_b64 v[80:81], 11, v[100:101]
	v_lshl_add_u64 v[80:81], s[60:61], 0, v[80:81]
	v_add_u32_e32 v102, 0xb0, v144
	v_lshl_add_u64 v[88:89], v[80:81], 0, v[146:147]
	v_ashrrev_i32_e32 v103, 31, v102
	v_lshlrev_b64 v[88:89], 11, v[102:103]
	v_lshl_add_u64 v[88:89], s[60:61], 0, v[88:89]
	v_lshl_add_u64 v[92:93], v[88:89], 0, v[146:147]
	global_load_dwordx4 v[88:91], v[92:93], off
	s_nop 0
	global_load_dwordx4 v[92:95], v[92:93], off offset:256
	s_waitcnt vmcnt(18)
	v_mov_b32_e32 v64, v228
	v_mov_b32_e32 v65, v229
	v_mov_b32_e32 v66, v230
	v_mov_b32_e32 v67, v231
	v_mov_b32_e32 v68, v232
	v_mov_b32_e32 v69, v233
	v_mov_b32_e32 v70, v234
	v_mov_b32_e32 v71, v235
	v_mov_b32_e32 v72, v236
	v_mov_b32_e32 v73, v237
	v_mov_b32_e32 v74, v238
	v_mov_b32_e32 v75, v239
	v_mov_b32_e32 v76, v240
	v_mov_b32_e32 v77, v241
	v_mov_b32_e32 v78, v242
	v_mov_b32_e32 v79, v243
	v_mov_b32_e32 v80, v244
	v_mov_b32_e32 v81, v245
	v_mov_b32_e32 v82, v246
	v_mov_b32_e32 v83, v247
	v_mov_b32_e32 v84, v248
	v_mov_b32_e32 v85, v249
	v_mov_b32_e32 v86, v250
	v_mov_b32_e32 v87, v251
	v_lshlrev_b64 v[96:97], 12, v[96:97]
	s_waitcnt vmcnt(7)
	v_lshlrev_b32_e32 v104, 16, v64
	v_and_b32_e32 v105, 0xffff0000, v64
	v_lshlrev_b32_e32 v64, 16, v65
	v_and_b32_e32 v65, 0xffff0000, v65
	s_waitcnt vmcnt(6)
	v_lshlrev_b32_e32 v108, 16, v68
	v_and_b32_e32 v109, 0xffff0000, v68
	v_lshlrev_b32_e32 v68, 16, v69
	v_and_b32_e32 v69, 0xffff0000, v69
	v_pk_fma_f32 v[62:63], v[62:63], 0.5, v[64:65] op_sel_hi:[1,0,1]
	v_lshl_add_u64 v[64:65], s[52:53], 0, v[96:97]
	v_lshlrev_b32_e32 v106, 16, v66
	v_and_b32_e32 v107, 0xffff0000, v66
	v_lshlrev_b32_e32 v66, 16, v67
	v_and_b32_e32 v67, 0xffff0000, v67
	v_lshlrev_b32_e32 v110, 16, v70
	v_and_b32_e32 v111, 0xffff0000, v70
	v_lshlrev_b32_e32 v70, 16, v71
	v_and_b32_e32 v71, 0xffff0000, v71
	v_pk_fma_f32 v[60:61], v[60:61], 0.5, v[104:105] op_sel_hi:[1,0,1]
	v_lshl_add_u64 v[64:65], v[64:65], 0, v[120:121]
	v_pk_fma_f32 v[54:55], v[54:55], 0.5, v[68:69] op_sel_hi:[1,0,1]
	v_pk_fma_f32 v[52:53], v[52:53], 0.5, v[108:109] op_sel_hi:[1,0,1]
	s_waitcnt vmcnt(5)
; __device__ __forceinline__ unsigned cvt_pk_bf16(float lo, float hi) { unsigned r; asm("v_cvt_pk_bf16_f32 %0, %1, %2" : "=v"(r) : "v"(lo), "v"(hi)); return r; }
; #define PG8_BAR __builtin_amdgcn_s_barrier()
; template <class Epi, class Sched>
; __device__ __forceinline__ void gemm_phase(LAS unsigned char* lds, const int lda, const int ldb, const int K, const Sched& S, const Epi& E) {
;     ...
;         if (wr == 0) PG8_BAR;
;         const bool keep = E(acc, cur, wr, wc, fr, fq, rsv);
;         if (!has_next) break;
;         if (!keep) {
; #pragma unroll
;             for (int a = 0; a < 2; ++a)
; #pragma unroll
;                 for (int b = 0; b < 2; ++b)
; #pragma unroll
;                     for (int m = 0; m < 4; ++m)
; #pragma unroll
;                         for (int n = 0; n < 2; ++n) acc[a][b][m][n] = (f32x4){0.f, 0.f, 0.f, 0.f};
;         }
;         cur = nxt; cA = nA; cB = nB; ++ui;
;         if (wr == 1) PG8_BAR;
;     __device__ __forceinline__ bool operator()(AccT& acc, const pg8::Unit& u, int wr, int wc, int fr, int fq, const float (&)[8]) const {
;     ...
;             for (int m = 0; m < 4; ++m) {
;                 const int row = row0 + ai * 128 + m * 16; float sq = 0.f;
; #pragma unroll
;                 for (int bj = 0; bj < 2; ++bj) {
;                     const int col = colt + bj * 128; const float sc = (MODE == 1) ? 1.f : 0.5f;
;                     const f32x4 v0 = xv[m][bj][0] + sc * acc[ai][bj][m][0], v1 = xv[m][bj][1] + sc * acc[ai][bj][m][1];
;                     if (MODE == 2) { float* o = out + (size_t)row * D + col; __builtin_nontemporal_store(v0, (f32x4*)o); __builtin_nontemporal_store(v1, (f32x4*)(o + 4)); }
;                     if (MODE != 2) {
;                         sq += (v0[0] * v0[0] + v0[1] * v0[1]) + (v0[2] * v0[2] + v0[3] * v0[3]) + (v1[0] * v1[0] + v1[1] * v1[1]) + (v1[2] * v1[2] + v1[3] * v1[3]);
;                         u32x4 w; w.x = cvt_pk_bf16(v0[0], v0[1]); w.y = cvt_pk_bf16(v0[2], v0[3]); w.z = cvt_pk_bf16(v1[0], v1[1]); w.w = cvt_pk_bf16(v1[2], v1[3]);
;                         *(u32x4*)(xb + (size_t)row * D + col) = w; }
	v_lshlrev_b32_e32 v112, 16, v72
	v_and_b32_e32 v113, 0xffff0000, v72
	v_pk_fma_f32 v[58:59], v[58:59], 0.5, v[66:67] op_sel_hi:[1,0,1]
	v_pk_fma_f32 v[56:57], v[56:57], 0.5, v[106:107] op_sel_hi:[1,0,1]
	global_store_dwordx4 v[64:65], v[60:63], off nt
	global_store_dwordx4 v[64:65], v[56:59], off offset:16 nt
	v_pk_fma_f32 v[46:47], v[46:47], 0.5, v[70:71] op_sel_hi:[1,0,1]
	v_pk_fma_f32 v[44:45], v[44:45], 0.5, v[110:111] op_sel_hi:[1,0,1]
	global_store_dwordx4 v[64:65], v[52:55], off offset:512 nt
	global_store_dwordx4 v[64:65], v[44:47], off offset:528 nt
	v_lshlrev_b32_e32 v72, 16, v73
	v_lshlrev_b64 v[52:53], 12, v[98:99]
	v_and_b32_e32 v73, 0xffff0000, v73
	s_waitcnt vmcnt(8)
	v_lshlrev_b32_e32 v116, 16, v76
	v_and_b32_e32 v117, 0xffff0000, v76
	v_lshlrev_b32_e32 v76, 16, v77
	v_and_b32_e32 v77, 0xffff0000, v77
	v_pk_fma_f32 v[44:45], v[48:49], 0.5, v[112:113] op_sel_hi:[1,0,1]
	v_lshl_add_u64 v[48:49], s[52:53], 0, v[52:53]
	v_lshlrev_b32_e32 v114, 16, v74
	v_and_b32_e32 v115, 0xffff0000, v74
	v_lshlrev_b32_e32 v74, 16, v75
	v_and_b32_e32 v75, 0xffff0000, v75
	v_lshlrev_b32_e32 v118, 16, v78
	v_and_b32_e32 v119, 0xffff0000, v78
	v_lshlrev_b32_e32 v78, 16, v79
	v_and_b32_e32 v79, 0xffff0000, v79
	v_pk_fma_f32 v[46:47], v[50:51], 0.5, v[72:73] op_sel_hi:[1,0,1]
	v_lshl_add_u64 v[48:49], v[48:49], 0, v[120:121]
	v_pk_fma_f32 v[38:39], v[38:39], 0.5, v[76:77] op_sel_hi:[1,0,1]
	v_pk_fma_f32 v[36:37], v[36:37], 0.5, v[116:117] op_sel_hi:[1,0,1]
	s_waitcnt vmcnt(7)
	v_lshlrev_b32_e32 v122, 16, v80
	v_and_b32_e32 v123, 0xffff0000, v80
	v_pk_fma_f32 v[42:43], v[42:43], 0.5, v[74:75] op_sel_hi:[1,0,1]
	v_pk_fma_f32 v[40:41], v[40:41], 0.5, v[114:115] op_sel_hi:[1,0,1]
	global_store_dwordx4 v[48:49], v[44:47], off nt
	global_store_dwordx4 v[48:49], v[40:43], off offset:16 nt
	v_pk_fma_f32 v[30:31], v[30:31], 0.5, v[78:79] op_sel_hi:[1,0,1]
	v_pk_fma_f32 v[28:29], v[28:29], 0.5, v[118:119] op_sel_hi:[1,0,1]
	global_store_dwordx4 v[48:49], v[36:39], off offset:512 nt
	global_store_dwordx4 v[48:49], v[28:31], off offset:528 nt
	v_lshlrev_b32_e32 v80, 16, v81
	v_lshlrev_b64 v[36:37], 12, v[100:101]
	v_and_b32_e32 v81, 0xffff0000, v81
	s_waitcnt vmcnt(10)
	v_lshlrev_b32_e32 v126, 16, v84
	v_and_b32_e32 v127, 0xffff0000, v84
	v_lshlrev_b32_e32 v84, 16, v85
	v_and_b32_e32 v85, 0xffff0000, v85
	v_pk_fma_f32 v[28:29], v[32:33], 0.5, v[122:123] op_sel_hi:[1,0,1]
	v_lshl_add_u64 v[32:33], s[52:53], 0, v[36:37]
	v_lshlrev_b32_e32 v124, 16, v82
	v_and_b32_e32 v125, 0xffff0000, v82
	v_lshlrev_b32_e32 v82, 16, v83
	v_and_b32_e32 v83, 0xffff0000, v83
	v_lshlrev_b32_e32 v144, 16, v86
	v_and_b32_e32 v145, 0xffff0000, v86
	v_lshlrev_b32_e32 v86, 16, v87
	v_and_b32_e32 v87, 0xffff0000, v87
	v_pk_fma_f32 v[30:31], v[34:35], 0.5, v[80:81] op_sel_hi:[1,0,1]
	v_lshl_add_u64 v[32:33], v[32:33], 0, v[120:121]
	v_pk_fma_f32 v[22:23], v[22:23], 0.5, v[84:85] op_sel_hi:[1,0,1]
	v_pk_fma_f32 v[20:21], v[20:21], 0.5, v[126:127] op_sel_hi:[1,0,1]
	s_waitcnt vmcnt(9)
	v_lshlrev_b32_e32 v146, 16, v88
	v_and_b32_e32 v147, 0xffff0000, v88
	v_pk_fma_f32 v[26:27], v[26:27], 0.5, v[82:83] op_sel_hi:[1,0,1]
	v_pk_fma_f32 v[24:25], v[24:25], 0.5, v[124:125] op_sel_hi:[1,0,1]
	global_store_dwordx4 v[32:33], v[28:31], off nt
	global_store_dwordx4 v[32:33], v[24:27], off offset:16 nt
	v_pk_fma_f32 v[14:15], v[14:15], 0.5, v[86:87] op_sel_hi:[1,0,1]
	v_pk_fma_f32 v[12:13], v[12:13], 0.5, v[144:145] op_sel_hi:[1,0,1]
	global_store_dwordx4 v[32:33], v[20:23], off offset:512 nt
	global_store_dwordx4 v[32:33], v[12:15], off offset:528 nt
	v_lshlrev_b32_e32 v88, 16, v89
	v_lshlrev_b64 v[20:21], 12, v[102:103]
	v_and_b32_e32 v89, 0xffff0000, v89
	s_waitcnt vmcnt(12)
	v_lshlrev_b32_e32 v156, 16, v92
	v_and_b32_e32 v157, 0xffff0000, v92
	v_lshlrev_b32_e32 v92, 16, v93
	v_and_b32_e32 v93, 0xffff0000, v93
	v_pk_fma_f32 v[12:13], v[16:17], 0.5, v[146:147] op_sel_hi:[1,0,1]
	v_lshl_add_u64 v[16:17], s[52:53], 0, v[20:21]
	v_lshlrev_b32_e32 v154, 16, v90
	v_and_b32_e32 v155, 0xffff0000, v90
	v_lshlrev_b32_e32 v90, 16, v91
	v_and_b32_e32 v91, 0xffff0000, v91
	v_lshlrev_b32_e32 v158, 16, v94
	v_and_b32_e32 v159, 0xffff0000, v94
	v_lshlrev_b32_e32 v94, 16, v95
	v_and_b32_e32 v95, 0xffff0000, v95
	v_pk_fma_f32 v[14:15], v[18:19], 0.5, v[88:89] op_sel_hi:[1,0,1]
	v_lshl_add_u64 v[16:17], v[16:17], 0, v[120:121]
	v_pk_fma_f32 v[6:7], v[6:7], 0.5, v[92:93] op_sel_hi:[1,0,1]
	v_pk_fma_f32 v[4:5], v[4:5], 0.5, v[156:157] op_sel_hi:[1,0,1]
	v_pk_fma_f32 v[10:11], v[10:11], 0.5, v[90:91] op_sel_hi:[1,0,1]
	v_pk_fma_f32 v[8:9], v[8:9], 0.5, v[154:155] op_sel_hi:[1,0,1]
	global_store_dwordx4 v[16:17], v[12:15], off nt
	global_store_dwordx4 v[16:17], v[8:11], off offset:16 nt
	v_pk_fma_f32 v[2:3], v[2:3], 0.5, v[94:95] op_sel_hi:[1,0,1]
	v_pk_fma_f32 v[0:1], v[0:1], 0.5, v[158:159] op_sel_hi:[1,0,1]
	global_store_dwordx4 v[16:17], v[4:7], off offset:512 nt
	global_store_dwordx4 v[16:17], v[0:3], off offset:528 nt
	s_cbranch_vccnz .LBB0_1132
	s_andn2_b64 vcc, exec, s[4:5]
	s_cbranch_vccnz .LBB0_1131
	s_barrier
	s_branch .LBB0_1131
